# pp_v17 + RC1 S2: six tile operand reads issued at once; forward-substitution L rows read ~6 reads ahead through rotating register slots
# baseline (speedup 1.0000x reference)
.LBB0_1103:
	v_cvt_pk_bf16_f32 v1, v1, s0
	v_add_u32_e32 v30, s42, v157
	ds_write_b16 v30, v1
	ds_read_b128 v[30:33], v190 offset:27648
	ds_read_b128 v[34:37], v190 offset:27712
	s_andn2_b64 vcc, exec, s[58:59]
	s_waitcnt lgkmcnt(6)
	v_mfma_f32_16x16x32_bf16 v[22:25], v[18:21], v[22:25], 0
	s_waitcnt lgkmcnt(6)
	v_mfma_f32_16x16x32_bf16 v[22:25], v[14:17], v[26:29], v[22:25]
	s_nop 7
	v_cvt_pk_bf16_f32 v1, v22, s0
	v_cndmask_b32_e64 v1, 0, v1, s[8:9]
	v_add_u32_e32 v22, s43, v140
	ds_write_b16 v22, v1
	v_cvt_pk_bf16_f32 v1, v23, s0
	v_cndmask_b32_e64 v1, v1, 0, s[10:11]
	v_add_u32_e32 v22, s43, v141
	ds_write_b16 v22, v1
	v_cvt_pk_bf16_f32 v1, v24, s0
	v_cndmask_b32_e64 v1, 0, v1, s[12:13]
	v_add_u32_e32 v22, s43, v142
	ds_write_b16 v22, v1
	v_cvt_pk_bf16_f32 v1, v25, s0
	v_cndmask_b32_e64 v1, 0, v1, s[14:15]
	v_add_u32_e32 v22, s43, v143
	ds_write_b16 v22, v1
	ds_read_b128 v[22:25], v192 offset:27648
	ds_read_b128 v[26:29], v192 offset:27712
	s_waitcnt lgkmcnt(6)
	v_mfma_f32_16x16x32_bf16 v[30:33], v[18:21], v[30:33], 0
	s_waitcnt lgkmcnt(6)
	v_mfma_f32_16x16x32_bf16 v[30:33], v[14:17], v[34:37], v[30:33]
	s_nop 7
	v_cvt_pk_bf16_f32 v1, v30, s0
	v_cndmask_b32_e64 v1, 0, v1, s[16:17]
	v_add_u32_e32 v30, s43, v145
	ds_write_b16 v30, v1
	v_cvt_pk_bf16_f32 v1, v31, s0
	v_cndmask_b32_e64 v1, v1, 0, s[18:19]
	v_add_u32_e32 v30, s43, v146
	ds_write_b16 v30, v1
	v_cvt_pk_bf16_f32 v1, v32, s0
	v_cndmask_b32_e64 v1, 0, v1, s[20:21]
	v_add_u32_e32 v30, s43, v147
	ds_write_b16 v30, v1
	v_cvt_pk_bf16_f32 v1, v33, s0
	v_cndmask_b32_e64 v1, 0, v1, s[22:23]
	v_add_u32_e32 v30, s43, v149
	ds_write_b16 v30, v1
	ds_read_b128 v[30:33], v193 offset:27648
	ds_read_b128 v[34:37], v193 offset:27712
	s_waitcnt lgkmcnt(6)
	v_mfma_f32_16x16x32_bf16 v[22:25], v[18:21], v[22:25], 0
	s_waitcnt lgkmcnt(6)
	v_mfma_f32_16x16x32_bf16 v[22:25], v[14:17], v[26:29], v[22:25]
	v_add_u32_e32 v26, v118, v120
	s_nop 6
	v_cvt_pk_bf16_f32 v1, v22, s0
	v_cndmask_b32_e64 v1, 0, v1, s[24:25]
	v_add_u32_e32 v22, s43, v150
	ds_write_b16 v22, v1
	v_cvt_pk_bf16_f32 v1, v23, s0
	v_cndmask_b32_e64 v1, v1, 0, s[26:27]
	v_add_u32_e32 v22, s43, v151
	ds_write_b16 v22, v1
	v_cvt_pk_bf16_f32 v1, v24, s0
	v_cndmask_b32_e64 v1, 0, v1, s[28:29]
	v_add_u32_e32 v22, s43, v152
	ds_write_b16 v22, v1
	v_cvt_pk_bf16_f32 v1, v25, s0
	v_cndmask_b32_e64 v1, 0, v1, s[30:31]
	v_add_u32_e32 v22, s43, v153
	ds_write_b16 v22, v1
	s_waitcnt lgkmcnt(4)
	v_mfma_f32_16x16x32_bf16 v[30:33], v[18:21], v[30:33], 0
	v_mfma_f32_16x16x32_bf16 v[30:33], v[14:17], v[34:37], v[30:33]
	s_nop 7
	v_cvt_pk_bf16_f32 v1, v30, s0
	v_cndmask_b32_e64 v1, 0, v1, s[34:35]
	v_add_u32_e32 v30, s43, v154
	ds_write_b16 v30, v1
	v_cvt_pk_bf16_f32 v1, v31, s0
	v_cndmask_b32_e64 v1, v1, 0, s[36:37]
	v_add_u32_e32 v30, s43, v155
	ds_write_b16 v30, v1
	v_cvt_pk_bf16_f32 v1, v32, s0
	v_cndmask_b32_e64 v1, 0, v1, s[38:39]
	v_add_u32_e32 v30, s43, v156
	ds_write_b16 v30, v1
	v_cvt_pk_bf16_f32 v1, v33, s0
	v_cndmask_b32_e64 v1, 0, v1, s[40:41]
	v_add_u32_e32 v30, s43, v157
	ds_write_b16 v30, v1
	v_add_u32_e32 v1, v118, v106
	s_waitcnt lgkmcnt(0)
	s_barrier
	ds_read_b128 v[14:17], v1 offset:64512
	ds_read_b128 v[18:21], v179 offset:55296
	ds_read_b128 v[38:41], v182 offset:55296
	ds_read_b128 v[22:25], v26 offset:64512
	ds_read_b128 v[30:33], v180 offset:55296
	ds_read_b128 v[34:37], v183 offset:55296
	s_waitcnt lgkmcnt(3)
	v_mfma_f32_16x16x32_bf16 v[42:45], v[14:17], v[18:21], 0
	v_mfma_f32_16x16x32_bf16 v[46:49], v[14:17], v[38:41], 0
	s_waitcnt lgkmcnt(0)
	v_mfma_f32_16x16x32_bf16 v[42:45], v[22:25], v[30:33], v[42:45]
	v_mfma_f32_16x16x32_bf16 v[46:49], v[22:25], v[34:37], v[46:49]
	s_nop 7
	s_nop 1
	ds_write2_b32 v181, v42, v43 offset1:65
	ds_write2_b32 v181, v44, v45 offset0:130 offset1:195
	ds_write2_b32 v184, v46, v47 offset1:65
	ds_write2_b32 v184, v48, v49 offset0:130 offset1:195
	s_cbranch_vccnz .LBB0_1107
	v_mov_b32_e32 v29, s97
	v_mov_b32_e32 v14, v121
	ds_read_b128 v[30:33], v29 offset:64
	ds_read_b128 v[34:37], v29 offset:128
	ds_read_b128 v[38:41], v29 offset:192
	ds_read_b128 v[42:45], v29 offset:256
	ds_read_b128 v[46:49], v29 offset:320
	ds_read_b128 v[50:53], v29 offset:336
	ds_read_b128 v[54:57], v29 offset:384
	ds_read_b128 v[58:61], v29 offset:400
	s_waitcnt lgkmcnt(6)
	v_fma_f32 v1, -v14, v30, v122
	v_fma_f32 v15, -v14, v34, v123
	v_fma_f32 v15, -v1, v35, v15
	ds_read_b128 v[62:65], v29 offset:448
	ds_read_b128 v[66:69], v29 offset:464
	s_waitcnt lgkmcnt(6)
	v_fma_f32 v16, -v14, v38, v124
	v_fma_f32 v17, -v14, v42, v125
	v_fma_f32 v16, -v1, v39, v16
	v_fma_f32 v17, -v1, v43, v17
	v_fma_f32 v16, -v15, v40, v16
	v_fma_f32 v17, -v15, v44, v17
	v_fma_f32 v17, -v16, v45, v17
	ds_read_b128 v[70:73], v29 offset:512
	ds_read_b128 v[74:77], v29 offset:528
	ds_read_b128 v[78:81], v29 offset:576
	ds_read_b128 v[82:85], v29 offset:592
	s_waitcnt lgkmcnt(6)
	v_fma_f32 v18, -v14, v46, v126
	v_fma_f32 v19, -v14, v54, v127
	v_fma_f32 v18, -v1, v47, v18
	v_fma_f32 v19, -v1, v55, v19
	v_fma_f32 v18, -v15, v48, v18
	v_fma_f32 v19, -v15, v56, v19
	v_fma_f32 v18, -v16, v49, v18
	v_fma_f32 v19, -v16, v57, v19
	v_fma_f32 v18, -v17, v50, v18
	v_fma_f32 v19, -v17, v58, v19
	v_fma_f32 v19, -v18, v59, v19
	ds_read_b128 v[100:103], v29 offset:608
	ds_read_b128 v[228:231], v29 offset:640
	ds_read_b128 v[232:235], v29 offset:656
	ds_read_b128 v[248:251], v29 offset:672
	s_waitcnt lgkmcnt(6)
	v_fma_f32 v20, -v14, v62, v128
	v_fma_f32 v21, -v14, v70, v129
	v_fma_f32 v20, -v1, v63, v20
	v_fma_f32 v21, -v1, v71, v21
	v_fma_f32 v20, -v15, v64, v20
	v_fma_f32 v21, -v15, v72, v21
	v_fma_f32 v20, -v16, v65, v20
	v_fma_f32 v21, -v16, v73, v21
	v_fma_f32 v20, -v17, v66, v20
	v_fma_f32 v21, -v17, v74, v21
	v_fma_f32 v20, -v18, v67, v20
	v_fma_f32 v21, -v18, v75, v21
	v_fma_f32 v20, -v19, v68, v20
	v_fma_f32 v21, -v19, v76, v21
	v_fma_f32 v21, -v20, v77, v21
	ds_read_b128 v[252:255], v29 offset:704
	ds_read_b128 v[194:197], v29 offset:720
	ds_read_b128 v[30:33], v29 offset:736
	ds_read_b128 v[34:37], v29 offset:768
	ds_read_b128 v[38:41], v29 offset:784
	ds_read_b128 v[42:45], v29 offset:800
	s_waitcnt lgkmcnt(6)
	v_fma_f32 v22, -v14, v78, v130
	v_fma_f32 v23, -v14, v228, v131
	v_fma_f32 v22, -v1, v79, v22
	v_fma_f32 v23, -v1, v229, v23
	v_fma_f32 v22, -v15, v80, v22
	v_fma_f32 v23, -v15, v230, v23
	v_fma_f32 v22, -v16, v81, v22
	v_fma_f32 v23, -v16, v231, v23
	v_fma_f32 v22, -v17, v82, v22
	v_fma_f32 v23, -v17, v232, v23
	v_fma_f32 v22, -v18, v83, v22
	v_fma_f32 v23, -v18, v233, v23
	v_fma_f32 v22, -v19, v84, v22
	v_fma_f32 v23, -v19, v234, v23
	v_fma_f32 v22, -v20, v85, v22
	v_fma_f32 v23, -v20, v235, v23
	v_fma_f32 v22, -v21, v100, v22
	v_fma_f32 v23, -v21, v248, v23
	v_fma_f32 v23, -v22, v249, v23
	ds_read_b128 v[46:49], v29 offset:832
	ds_read_b128 v[50:53], v29 offset:848
	ds_read_b128 v[54:57], v29 offset:864
	ds_read_b128 v[58:61], v29 offset:880
	ds_read_b128 v[62:65], v29 offset:896
	ds_read_b128 v[66:69], v29 offset:912
	s_waitcnt lgkmcnt(6)
	v_fma_f32 v24, -v14, v252, v132
	v_fma_f32 v25, -v14, v34, v133
	v_fma_f32 v24, -v1, v253, v24
	v_fma_f32 v25, -v1, v35, v25
	v_fma_f32 v24, -v15, v254, v24
	v_fma_f32 v25, -v15, v36, v25
	v_fma_f32 v24, -v16, v255, v24
	v_fma_f32 v25, -v16, v37, v25
	v_fma_f32 v24, -v17, v194, v24
	v_fma_f32 v25, -v17, v38, v25
	v_fma_f32 v24, -v18, v195, v24
	v_fma_f32 v25, -v18, v39, v25
	v_fma_f32 v24, -v19, v196, v24
	v_fma_f32 v25, -v19, v40, v25
	v_fma_f32 v24, -v20, v197, v24
	v_fma_f32 v25, -v20, v41, v25
	v_fma_f32 v24, -v21, v30, v24
	v_fma_f32 v25, -v21, v42, v25
	v_fma_f32 v24, -v22, v31, v24
	v_fma_f32 v25, -v22, v43, v25
	v_fma_f32 v24, -v23, v32, v24
	v_fma_f32 v25, -v23, v44, v25
	v_fma_f32 v25, -v24, v45, v25
	ds_read_b128 v[70:73], v29 offset:928
	ds_read_b128 v[74:77], v29 offset:944
	ds_read_b128 v[78:81], v29 offset:960
	ds_read_b128 v[82:85], v29 offset:976
	ds_read_b128 v[100:103], v29 offset:992
	ds_read_b128 v[228:231], v29 offset:1008
	s_waitcnt lgkmcnt(4)
	v_fma_f32 v26, -v14, v46, v134
	v_fma_f32 v27, -v14, v62, v135
	v_fma_f32 v26, -v1, v47, v26
	v_fma_f32 v27, -v1, v63, v27
	v_fma_f32 v26, -v15, v48, v26
	v_fma_f32 v27, -v15, v64, v27
	v_fma_f32 v26, -v16, v49, v26
	v_fma_f32 v27, -v16, v65, v27
	v_fma_f32 v26, -v17, v50, v26
	v_fma_f32 v27, -v17, v66, v27
	v_fma_f32 v26, -v18, v51, v26
	v_fma_f32 v27, -v18, v67, v27
	v_fma_f32 v26, -v19, v52, v26
	v_fma_f32 v27, -v19, v68, v27
	v_fma_f32 v26, -v20, v53, v26
	v_fma_f32 v27, -v20, v69, v27
	v_fma_f32 v26, -v21, v54, v26
	v_fma_f32 v27, -v21, v70, v27
	v_fma_f32 v26, -v22, v55, v26
	v_fma_f32 v27, -v22, v71, v27
	v_fma_f32 v26, -v23, v56, v26
	v_fma_f32 v27, -v23, v72, v27
	v_fma_f32 v26, -v24, v57, v26
	v_fma_f32 v27, -v24, v73, v27
	v_fma_f32 v26, -v25, v58, v26
	v_fma_f32 v27, -v25, v74, v27
	v_fma_f32 v27, -v26, v75, v27
	s_waitcnt lgkmcnt(0)
	v_fma_f32 v28, -v14, v78, v136
	v_fma_f32 v28, -v1, v79, v28
	v_fma_f32 v28, -v15, v80, v28
	v_fma_f32 v28, -v16, v81, v28
	v_fma_f32 v28, -v17, v82, v28
	v_fma_f32 v28, -v18, v83, v28
	v_fma_f32 v28, -v19, v84, v28
	v_fma_f32 v28, -v20, v85, v28
	v_fma_f32 v28, -v21, v100, v28
	v_fma_f32 v28, -v22, v101, v28
	v_fma_f32 v28, -v23, v102, v28
	v_fma_f32 v28, -v24, v103, v28
	v_fma_f32 v28, -v25, v228, v28
	v_fma_f32 v28, -v26, v229, v28
	v_fma_f32 v28, -v27, v230, v28
	s_and_saveexec_b64 s[0:1], s[6:7]
	s_cbranch_execz .LBB0_1106
	v_readlane_b32 s2, v238, 39
	v_cvt_pk_bf16_f32 v14, v14, s0
	v_cvt_pk_bf16_f32 v1, v1, s0
	v_add_u32_e32 v29, s2, v158
	v_readlane_b32 s2, v238, 43
	ds_write_b16 v29, v14
	s_nop 0
	v_add_u32_e32 v14, s2, v158
	v_readlane_b32 s2, v238, 49
	ds_write_b16 v14, v1
	v_cvt_pk_bf16_f32 v1, v15, s0
	v_add_u32_e32 v14, s2, v158
	v_readlane_b32 s2, v238, 50
	ds_write_b16 v14, v1
	v_cvt_pk_bf16_f32 v1, v16, s0
	v_add_u32_e32 v14, s2, v158
	v_readlane_b32 s2, v238, 51
	ds_write_b16 v14, v1
	v_cvt_pk_bf16_f32 v1, v17, s0
	v_add_u32_e32 v14, s2, v158
	v_readlane_b32 s2, v238, 52
	ds_write_b16 v14, v1
	v_cvt_pk_bf16_f32 v1, v18, s0
	v_add_u32_e32 v14, s2, v158
	v_readlane_b32 s2, v238, 53
	ds_write_b16 v14, v1
	v_cvt_pk_bf16_f32 v1, v19, s0
	v_add_u32_e32 v14, s2, v158
	v_readlane_b32 s2, v238, 54
	ds_write_b16 v14, v1
	v_cvt_pk_bf16_f32 v1, v20, s0
	v_add_u32_e32 v14, s2, v158
	v_readlane_b32 s2, v238, 55
	ds_write_b16 v14, v1
	v_cvt_pk_bf16_f32 v1, v21, s0
	v_add_u32_e32 v14, s2, v158
	v_readlane_b32 s2, v238, 56
	ds_write_b16 v14, v1
	v_cvt_pk_bf16_f32 v1, v22, s0
	v_add_u32_e32 v14, s2, v158
	v_readlane_b32 s2, v238, 57
	ds_write_b16 v14, v1
	v_cvt_pk_bf16_f32 v1, v23, s0
	v_add_u32_e32 v14, s2, v158
	ds_write_b16 v14, v1
	v_cvt_pk_bf16_f32 v1, v24, s0
	v_add_u32_e32 v14, s92, v158
	ds_write_b16 v14, v1
	v_cvt_pk_bf16_f32 v1, v25, s0
	v_add_u32_e32 v14, s86, v158
	ds_write_b16 v14, v1
	v_cvt_pk_bf16_f32 v1, v26, s0
	v_add_u32_e32 v14, s33, v158
	ds_write_b16 v14, v1
	v_cvt_pk_bf16_f32 v1, v27, s0
	v_add_u32_e32 v14, s50, v158
	ds_write_b16 v14, v1
	v_cvt_pk_bf16_f32 v1, v28, s0
	v_add_u32_e32 v14, s51, v158
	ds_write_b16 v14, v1
